# post phase fast path: 16 lanes x 4 channels per item, wide loads, write-through stores; plus scan loop rewrite
# speedup vs baseline: 1.0037x; 1.0037x over previous
; __device__ __forceinline__ float bf2f(bf16 b) { return (float)__builtin_bit_cast(_Float16, b); }
; __device__ __forceinline__ void post_phase(const Ctx& F, const float* gn_g, const float* gn_b) {
;     ...
;     for (int it0 = F.gw * 4; it0 < M * NH; it0 += F.NGW * 4) {
;         float y[4], bsv[4], vv[4], gg[4]; int cc[4]; size_t oo[4];
; #pragma unroll
;         for (int u = 0; u < 4; ++u) { const int it = it0 + u; const int tok = it >> 3, head = it & 7; const int bh = (tok / SEQ) * NH + head, pos = tok & (SEQ - 1);
;             const size_t idx = ((size_t)bh * SEQ + pos) * 64 + lane; cc[u] = head * 64 + lane; oo[u] = (size_t)tok * 1024 + 512 + cc[u];
;             y[u] = Y[idx]; bsv[u] = SCAL[((size_t)bh * SEQ + pos) * 2 + 1]; vv[u] = bf2f(SV[idx]); gg[u] = bf2f(GG[(size_t)tok * 512 + cc[u]]); }
.LBB0_769:
	s_cmp_lt_i32 s74, 8
	s_cselect_b64 s[2:3], -1, 0
	s_and_b64 s[2:3], s[2:3], s[0:1]
	s_andn2_b64 vcc, exec, s[2:3]
	s_cbranch_vccnz .LBB0_773
	s_cmp_gt_i32 s87, 0xffff
	s_cbranch_scc1 .LBB0_773
	v_readlane_b32 s6, v253, 1
	s_nop 3
	s_cmpk_lg_i32 s6, 0x100
	s_cbranch_scc1 .Lpost_orig
	s_add_u32 s4, s72, 0x1ac00000
	s_addc_u32 s5, s73, 0
	s_add_u32 s6, s72, 0x8c00000
	s_addc_u32 s7, s73, 0
	s_add_u32 s8, s72, 0x14c00000
	s_addc_u32 s9, s73, 0
	s_add_u32 s10, s72, 0x1ec00004
	s_addc_u32 s11, s73, 0
	s_add_u32 s12, s72, 0x16c00400
	s_addc_u32 s13, s73, 0
	s_and_b32 s16, s87, 1
	s_lshl_b32 s16, s16, 2
	v_lshrrev_b32_e32 v16, 4, v162
	v_and_b32_e32 v17, 15, v162
	v_add_u32_e32 v16, s16, v16
	v_lshlrev_b32_e32 v1, 20, v16
	v_lshl_add_u32 v1, v17, 4, v1
	v_lshlrev_b32_e32 v2, 19, v16
	v_lshl_add_u32 v2, v17, 3, v2
	v_lshlrev_b32_e32 v3, 15, v16
	v_lshlrev_b32_e32 v4, 7, v16
	v_lshl_add_u32 v4, v17, 3, v4
	v_lshlrev_b32_e32 v18, 8, v16
	v_lshl_add_u32 v18, v17, 4, v18
	global_load_dwordx4 v[6:9], v18, s[62:63]
	global_load_dwordx4 v[10:13], v18, s[64:65]
	v_mov_b32_e32 v14, 0xbc800000
	v_mov_b32_e32 v15, 0x3c800000
	v_mov_b32_e32 v19, 0x3a27c5ac
	s_lshr_b32 s14, s87, 1
	s_mov_b32 s15, 0
.Lpost_iter:
	s_add_i32 s16, s14, 0
	s_lshr_b32 s17, s16, 12
	s_mul_i32 s18, s17, 0x7000
	s_add_i32 s18, s18, s16
	s_lshl_b32 s19, s18, 8
	s_add_u32 s20, s4, s19
	s_addc_u32 s21, s5, 0
	global_load_dwordx4 v[20:23], v1, s[20:21]
	s_lshl_b32 s19, s18, 7
	s_add_u32 s22, s6, s19
	s_addc_u32 s23, s7, 0
	global_load_dwordx2 v[24:25], v2, s[22:23]
	s_lshl_b32 s19, s16, 10
	s_add_u32 s24, s8, s19
	s_addc_u32 s25, s9, 0
	global_load_dwordx2 v[26:27], v4, s[24:25]
	s_lshl_b32 s19, s18, 3
	s_add_u32 s20, s10, s19
	s_addc_u32 s21, s11, 0
	global_load_dword v28, v3, s[20:21]
	s_add_i32 s16, s14, 1024
	s_lshr_b32 s17, s16, 12
	s_mul_i32 s18, s17, 0x7000
	s_add_i32 s18, s18, s16
	s_lshl_b32 s19, s18, 8
	s_add_u32 s20, s4, s19
	s_addc_u32 s21, s5, 0
	global_load_dwordx4 v[30:33], v1, s[20:21]
	s_lshl_b32 s19, s18, 7
	s_add_u32 s22, s6, s19
	s_addc_u32 s23, s7, 0
	global_load_dwordx2 v[34:35], v2, s[22:23]
	s_lshl_b32 s19, s16, 10
	s_add_u32 s24, s8, s19
	s_addc_u32 s25, s9, 0
	global_load_dwordx2 v[36:37], v4, s[24:25]
	s_lshl_b32 s19, s18, 3
	s_add_u32 s20, s10, s19
	s_addc_u32 s21, s11, 0
	global_load_dword v38, v3, s[20:21]
	s_add_i32 s16, s14, 2048
	s_lshr_b32 s17, s16, 12
	s_mul_i32 s18, s17, 0x7000
	s_add_i32 s18, s18, s16
	s_lshl_b32 s19, s18, 8
	s_add_u32 s20, s4, s19
	s_addc_u32 s21, s5, 0
	global_load_dwordx4 v[40:43], v1, s[20:21]
	s_lshl_b32 s19, s18, 7
	s_add_u32 s22, s6, s19
	s_addc_u32 s23, s7, 0
	global_load_dwordx2 v[44:45], v2, s[22:23]
	s_lshl_b32 s19, s16, 10
	s_add_u32 s24, s8, s19
	s_addc_u32 s25, s9, 0
	global_load_dwordx2 v[46:47], v4, s[24:25]
	s_lshl_b32 s19, s18, 3
	s_add_u32 s20, s10, s19
	s_addc_u32 s21, s11, 0
	global_load_dword v48, v3, s[20:21]
	s_add_i32 s16, s14, 3072
	s_lshr_b32 s17, s16, 12
	s_mul_i32 s18, s17, 0x7000
	s_add_i32 s18, s18, s16
	s_lshl_b32 s19, s18, 8
	s_add_u32 s20, s4, s19
	s_addc_u32 s21, s5, 0
	global_load_dwordx4 v[50:53], v1, s[20:21]
	s_lshl_b32 s19, s18, 7
	s_add_u32 s22, s6, s19
	s_addc_u32 s23, s7, 0
	global_load_dwordx2 v[54:55], v2, s[22:23]
	s_lshl_b32 s19, s16, 10
	s_add_u32 s24, s8, s19
	s_addc_u32 s25, s9, 0
	global_load_dwordx2 v[56:57], v4, s[24:25]
	s_lshl_b32 s19, s18, 3
	s_add_u32 s20, s10, s19
	s_addc_u32 s21, s11, 0
	global_load_dword v58, v3, s[20:21]
	s_add_i32 s16, s14, 4096
	s_lshr_b32 s17, s16, 12
	s_mul_i32 s18, s17, 0x7000
	s_add_i32 s18, s18, s16
	s_lshl_b32 s19, s18, 8
	s_add_u32 s20, s4, s19
	s_addc_u32 s21, s5, 0
	global_load_dwordx4 v[60:63], v1, s[20:21]
	s_lshl_b32 s19, s18, 7
	s_add_u32 s22, s6, s19
	s_addc_u32 s23, s7, 0
	global_load_dwordx2 v[64:65], v2, s[22:23]
	s_lshl_b32 s19, s16, 10
	s_add_u32 s24, s8, s19
	s_addc_u32 s25, s9, 0
	global_load_dwordx2 v[66:67], v4, s[24:25]
	s_lshl_b32 s19, s18, 3
	s_add_u32 s20, s10, s19
	s_addc_u32 s21, s11, 0
	global_load_dword v68, v3, s[20:21]
	s_add_i32 s16, s14, 5120
	s_lshr_b32 s17, s16, 12
	s_mul_i32 s18, s17, 0x7000
	s_add_i32 s18, s18, s16
	s_lshl_b32 s19, s18, 8
	s_add_u32 s20, s4, s19
	s_addc_u32 s21, s5, 0
	global_load_dwordx4 v[70:73], v1, s[20:21]
	s_lshl_b32 s19, s18, 7
	s_add_u32 s22, s6, s19
	s_addc_u32 s23, s7, 0
	global_load_dwordx2 v[74:75], v2, s[22:23]
	s_lshl_b32 s19, s16, 10
	s_add_u32 s24, s8, s19
	s_addc_u32 s25, s9, 0
	global_load_dwordx2 v[76:77], v4, s[24:25]
	s_lshl_b32 s19, s18, 3
	s_add_u32 s20, s10, s19
	s_addc_u32 s21, s11, 0
	global_load_dword v78, v3, s[20:21]
	s_add_i32 s16, s14, 6144
	s_lshr_b32 s17, s16, 12
	s_mul_i32 s18, s17, 0x7000
	s_add_i32 s18, s18, s16
	s_lshl_b32 s19, s18, 8
	s_add_u32 s20, s4, s19
	s_addc_u32 s21, s5, 0
	global_load_dwordx4 v[80:83], v1, s[20:21]
	s_lshl_b32 s19, s18, 7
	s_add_u32 s22, s6, s19
	s_addc_u32 s23, s7, 0
	global_load_dwordx2 v[84:85], v2, s[22:23]
	s_lshl_b32 s19, s16, 10
	s_add_u32 s24, s8, s19
	s_addc_u32 s25, s9, 0
	global_load_dwordx2 v[86:87], v4, s[24:25]
	s_lshl_b32 s19, s18, 3
	s_add_u32 s20, s10, s19
	s_addc_u32 s21, s11, 0
	global_load_dword v88, v3, s[20:21]
	s_add_i32 s16, s14, 7168
	s_lshr_b32 s17, s16, 12
	s_mul_i32 s18, s17, 0x7000
	s_add_i32 s18, s18, s16
	s_lshl_b32 s19, s18, 8
	s_add_u32 s20, s4, s19
	s_addc_u32 s21, s5, 0
	global_load_dwordx4 v[90:93], v1, s[20:21]
	s_lshl_b32 s19, s18, 7
	s_add_u32 s22, s6, s19
	s_addc_u32 s23, s7, 0
	global_load_dwordx2 v[94:95], v2, s[22:23]
	s_lshl_b32 s19, s16, 10
	s_add_u32 s24, s8, s19
	s_addc_u32 s25, s9, 0
	global_load_dwordx2 v[96:97], v4, s[24:25]
	s_lshl_b32 s19, s18, 3
	s_add_u32 s20, s10, s19
	s_addc_u32 s21, s11, 0
	global_load_dword v98, v3, s[20:21]
	s_waitcnt vmcnt(28)
; __device__ __forceinline__ bf16 f2bf(float f) { return (bf16)(pk2(f, 0.f) & 0xffffu); }
; __device__ __forceinline__ void post_phase(const Ctx& F, const float* gn_g, const float* gn_b) {
;     ...
;             const float mean = wave_sum_d(y[u]) * (1.f / 64.f); const float d = y[u] - mean; const float var = wave_sum_d(d * d) * (1.f / 64.f);
;             const float yn = d * rsqrtf(var + GN_EPS) * gn_g[cc[u]] + gn_b[cc[u]];
;             CAT[oo[u]] = f2bf((yn + bsv[u] * vv[u]) * gg[u]); }
	v_add_f32_e32 v100, v20, v21
	v_add_f32_e32 v101, v22, v23
	v_add_f32_e32 v100, v100, v101
	s_nop 1
	v_add_f32_dpp v100, v100, v100 quad_perm:[1,0,3,2] row_mask:0xf bank_mask:0xf bound_ctrl:1
	s_nop 1
	v_add_f32_dpp v100, v100, v100 quad_perm:[2,3,0,1] row_mask:0xf bank_mask:0xf bound_ctrl:1
	s_nop 1
	v_add_f32_dpp v100, v100, v100 row_half_mirror row_mask:0xf bank_mask:0xf bound_ctrl:1
	s_nop 1
	v_add_f32_dpp v100, v100, v100 row_mirror row_mask:0xf bank_mask:0xf bound_ctrl:1
	v_fmac_f32_e32 v20, v100, v14
	v_fmac_f32_e32 v21, v100, v14
	v_fmac_f32_e32 v22, v100, v14
	v_fmac_f32_e32 v23, v100, v14
	v_mul_f32_e32 v101, v20, v20
	v_mul_f32_e32 v102, v22, v22
	v_fmac_f32_e32 v101, v21, v21
	v_fmac_f32_e32 v102, v23, v23
	v_add_f32_e32 v101, v101, v102
	s_nop 1
	v_add_f32_dpp v101, v101, v101 quad_perm:[1,0,3,2] row_mask:0xf bank_mask:0xf bound_ctrl:1
	s_nop 1
	v_add_f32_dpp v101, v101, v101 quad_perm:[2,3,0,1] row_mask:0xf bank_mask:0xf bound_ctrl:1
	s_nop 1
	v_add_f32_dpp v101, v101, v101 row_half_mirror row_mask:0xf bank_mask:0xf bound_ctrl:1
	s_nop 1
	v_add_f32_dpp v101, v101, v101 row_mirror row_mask:0xf bank_mask:0xf bound_ctrl:1
	v_fma_f32 v101, v101, v15, v19
	v_rsq_f32_e32 v101, v101
	s_nop 0
	v_mul_f32_e32 v20, v20, v101
	v_mul_f32_e32 v21, v21, v101
	v_mul_f32_e32 v22, v22, v101
	v_mul_f32_e32 v23, v23, v101
	v_fma_f32 v20, v20, v6, v10
	v_fma_f32 v21, v21, v7, v11
	v_fma_f32 v22, v22, v8, v12
	v_fma_f32 v23, v23, v9, v13
	v_fma_mix_f32 v20, v28, v24, v20 op_sel_hi:[0,1,0]
	v_fma_mix_f32 v21, v28, v24, v21 op_sel:[0,1,0] op_sel_hi:[0,1,0]
	v_fma_mix_f32 v22, v28, v25, v22 op_sel_hi:[0,1,0]
	v_fma_mix_f32 v23, v28, v25, v23 op_sel:[0,1,0] op_sel_hi:[0,1,0]
	v_fma_mixlo_f16 v102, v20, v26, 0 op_sel_hi:[0,1,0]
	v_fma_mixlo_f16 v104, v21, v26, 0 op_sel:[0,1,0] op_sel_hi:[0,1,0]
	v_fma_mixlo_f16 v103, v22, v27, 0 op_sel_hi:[0,1,0]
	v_fma_mixlo_f16 v105, v23, v27, 0 op_sel:[0,1,0] op_sel_hi:[0,1,0]
	v_and_b32_e32 v102, 0xffff, v102
	v_and_b32_e32 v103, 0xffff, v103
	v_lshl_or_b32 v102, v104, 16, v102
	v_lshl_or_b32 v103, v105, 16, v103
	s_add_i32 s16, s14, 0
	s_lshl_b32 s19, s16, 11
	s_add_u32 s20, s12, s19
	s_addc_u32 s21, s13, 0
	global_store_dwordx2 v4, v[102:103], s[20:21] sc1
	s_waitcnt vmcnt(25)
	v_add_f32_e32 v100, v30, v31
	v_add_f32_e32 v101, v32, v33
	v_add_f32_e32 v100, v100, v101
	s_nop 1
	v_add_f32_dpp v100, v100, v100 quad_perm:[1,0,3,2] row_mask:0xf bank_mask:0xf bound_ctrl:1
	s_nop 1
	v_add_f32_dpp v100, v100, v100 quad_perm:[2,3,0,1] row_mask:0xf bank_mask:0xf bound_ctrl:1
	s_nop 1
	v_add_f32_dpp v100, v100, v100 row_half_mirror row_mask:0xf bank_mask:0xf bound_ctrl:1
	s_nop 1
	v_add_f32_dpp v100, v100, v100 row_mirror row_mask:0xf bank_mask:0xf bound_ctrl:1
	v_fmac_f32_e32 v30, v100, v14
	v_fmac_f32_e32 v31, v100, v14
	v_fmac_f32_e32 v32, v100, v14
	v_fmac_f32_e32 v33, v100, v14
	v_mul_f32_e32 v101, v30, v30
	v_mul_f32_e32 v102, v32, v32
	v_fmac_f32_e32 v101, v31, v31
	v_fmac_f32_e32 v102, v33, v33
	v_add_f32_e32 v101, v101, v102
	s_nop 1
	v_add_f32_dpp v101, v101, v101 quad_perm:[1,0,3,2] row_mask:0xf bank_mask:0xf bound_ctrl:1
	s_nop 1
	v_add_f32_dpp v101, v101, v101 quad_perm:[2,3,0,1] row_mask:0xf bank_mask:0xf bound_ctrl:1
	s_nop 1
	v_add_f32_dpp v101, v101, v101 row_half_mirror row_mask:0xf bank_mask:0xf bound_ctrl:1
	s_nop 1
	v_add_f32_dpp v101, v101, v101 row_mirror row_mask:0xf bank_mask:0xf bound_ctrl:1
	v_fma_f32 v101, v101, v15, v19
	v_rsq_f32_e32 v101, v101
	s_nop 0
	v_mul_f32_e32 v30, v30, v101
	v_mul_f32_e32 v31, v31, v101
	v_mul_f32_e32 v32, v32, v101
	v_mul_f32_e32 v33, v33, v101
	v_fma_f32 v30, v30, v6, v10
	v_fma_f32 v31, v31, v7, v11
	v_fma_f32 v32, v32, v8, v12
	v_fma_f32 v33, v33, v9, v13
	v_fma_mix_f32 v30, v38, v34, v30 op_sel_hi:[0,1,0]
	v_fma_mix_f32 v31, v38, v34, v31 op_sel:[0,1,0] op_sel_hi:[0,1,0]
	v_fma_mix_f32 v32, v38, v35, v32 op_sel_hi:[0,1,0]
	v_fma_mix_f32 v33, v38, v35, v33 op_sel:[0,1,0] op_sel_hi:[0,1,0]
	v_fma_mixlo_f16 v102, v30, v36, 0 op_sel_hi:[0,1,0]
	v_fma_mixlo_f16 v104, v31, v36, 0 op_sel:[0,1,0] op_sel_hi:[0,1,0]
	v_fma_mixlo_f16 v103, v32, v37, 0 op_sel_hi:[0,1,0]
	v_fma_mixlo_f16 v105, v33, v37, 0 op_sel:[0,1,0] op_sel_hi:[0,1,0]
	v_and_b32_e32 v102, 0xffff, v102
	v_and_b32_e32 v103, 0xffff, v103
	v_lshl_or_b32 v102, v104, 16, v102
	v_lshl_or_b32 v103, v105, 16, v103
	s_add_i32 s16, s14, 1024
	s_lshl_b32 s19, s16, 11
	s_add_u32 s20, s12, s19
	s_addc_u32 s21, s13, 0
	global_store_dwordx2 v4, v[102:103], s[20:21] sc1
	s_waitcnt vmcnt(22)
	v_add_f32_e32 v100, v40, v41
	v_add_f32_e32 v101, v42, v43
	v_add_f32_e32 v100, v100, v101
	s_nop 1
	v_add_f32_dpp v100, v100, v100 quad_perm:[1,0,3,2] row_mask:0xf bank_mask:0xf bound_ctrl:1
	s_nop 1
	v_add_f32_dpp v100, v100, v100 quad_perm:[2,3,0,1] row_mask:0xf bank_mask:0xf bound_ctrl:1
	s_nop 1
	v_add_f32_dpp v100, v100, v100 row_half_mirror row_mask:0xf bank_mask:0xf bound_ctrl:1
	s_nop 1
	v_add_f32_dpp v100, v100, v100 row_mirror row_mask:0xf bank_mask:0xf bound_ctrl:1
	v_fmac_f32_e32 v40, v100, v14
	v_fmac_f32_e32 v41, v100, v14
	v_fmac_f32_e32 v42, v100, v14
	v_fmac_f32_e32 v43, v100, v14
	v_mul_f32_e32 v101, v40, v40
	v_mul_f32_e32 v102, v42, v42
	v_fmac_f32_e32 v101, v41, v41
	v_fmac_f32_e32 v102, v43, v43
	v_add_f32_e32 v101, v101, v102
	s_nop 1
	v_add_f32_dpp v101, v101, v101 quad_perm:[1,0,3,2] row_mask:0xf bank_mask:0xf bound_ctrl:1
	s_nop 1
	v_add_f32_dpp v101, v101, v101 quad_perm:[2,3,0,1] row_mask:0xf bank_mask:0xf bound_ctrl:1
	s_nop 1
	v_add_f32_dpp v101, v101, v101 row_half_mirror row_mask:0xf bank_mask:0xf bound_ctrl:1
	s_nop 1
	v_add_f32_dpp v101, v101, v101 row_mirror row_mask:0xf bank_mask:0xf bound_ctrl:1
	v_fma_f32 v101, v101, v15, v19
	v_rsq_f32_e32 v101, v101
	s_nop 0
	v_mul_f32_e32 v40, v40, v101
	v_mul_f32_e32 v41, v41, v101
	v_mul_f32_e32 v42, v42, v101
	v_mul_f32_e32 v43, v43, v101
	v_fma_f32 v40, v40, v6, v10
	v_fma_f32 v41, v41, v7, v11
	v_fma_f32 v42, v42, v8, v12
	v_fma_f32 v43, v43, v9, v13
	v_fma_mix_f32 v40, v48, v44, v40 op_sel_hi:[0,1,0]
	v_fma_mix_f32 v41, v48, v44, v41 op_sel:[0,1,0] op_sel_hi:[0,1,0]
	v_fma_mix_f32 v42, v48, v45, v42 op_sel_hi:[0,1,0]
	v_fma_mix_f32 v43, v48, v45, v43 op_sel:[0,1,0] op_sel_hi:[0,1,0]
	v_fma_mixlo_f16 v102, v40, v46, 0 op_sel_hi:[0,1,0]
	v_fma_mixlo_f16 v104, v41, v46, 0 op_sel:[0,1,0] op_sel_hi:[0,1,0]
	v_fma_mixlo_f16 v103, v42, v47, 0 op_sel_hi:[0,1,0]
	v_fma_mixlo_f16 v105, v43, v47, 0 op_sel:[0,1,0] op_sel_hi:[0,1,0]
	v_and_b32_e32 v102, 0xffff, v102
	v_and_b32_e32 v103, 0xffff, v103
	v_lshl_or_b32 v102, v104, 16, v102
	v_lshl_or_b32 v103, v105, 16, v103
	s_add_i32 s16, s14, 2048
	s_lshl_b32 s19, s16, 11
	s_add_u32 s20, s12, s19
	s_addc_u32 s21, s13, 0
	global_store_dwordx2 v4, v[102:103], s[20:21] sc1
	s_waitcnt vmcnt(19)
; __device__ __forceinline__ bf16 f2bf(float f) { return (bf16)(pk2(f, 0.f) & 0xffffu); }
; __device__ __forceinline__ void post_phase(const Ctx& F, const float* gn_g, const float* gn_b) {
;     ...
;             const float mean = wave_sum_d(y[u]) * (1.f / 64.f); const float d = y[u] - mean; const float var = wave_sum_d(d * d) * (1.f / 64.f);
;             const float yn = d * rsqrtf(var + GN_EPS) * gn_g[cc[u]] + gn_b[cc[u]];
;             CAT[oo[u]] = f2bf((yn + bsv[u] * vv[u]) * gg[u]); }
	v_add_f32_e32 v100, v50, v51
	v_add_f32_e32 v101, v52, v53
	v_add_f32_e32 v100, v100, v101
	s_nop 1
	v_add_f32_dpp v100, v100, v100 quad_perm:[1,0,3,2] row_mask:0xf bank_mask:0xf bound_ctrl:1
	s_nop 1
	v_add_f32_dpp v100, v100, v100 quad_perm:[2,3,0,1] row_mask:0xf bank_mask:0xf bound_ctrl:1
	s_nop 1
	v_add_f32_dpp v100, v100, v100 row_half_mirror row_mask:0xf bank_mask:0xf bound_ctrl:1
	s_nop 1
	v_add_f32_dpp v100, v100, v100 row_mirror row_mask:0xf bank_mask:0xf bound_ctrl:1
	v_fmac_f32_e32 v50, v100, v14
	v_fmac_f32_e32 v51, v100, v14
	v_fmac_f32_e32 v52, v100, v14
	v_fmac_f32_e32 v53, v100, v14
	v_mul_f32_e32 v101, v50, v50
	v_mul_f32_e32 v102, v52, v52
	v_fmac_f32_e32 v101, v51, v51
	v_fmac_f32_e32 v102, v53, v53
	v_add_f32_e32 v101, v101, v102
	s_nop 1
	v_add_f32_dpp v101, v101, v101 quad_perm:[1,0,3,2] row_mask:0xf bank_mask:0xf bound_ctrl:1
	s_nop 1
	v_add_f32_dpp v101, v101, v101 quad_perm:[2,3,0,1] row_mask:0xf bank_mask:0xf bound_ctrl:1
	s_nop 1
	v_add_f32_dpp v101, v101, v101 row_half_mirror row_mask:0xf bank_mask:0xf bound_ctrl:1
	s_nop 1
	v_add_f32_dpp v101, v101, v101 row_mirror row_mask:0xf bank_mask:0xf bound_ctrl:1
	v_fma_f32 v101, v101, v15, v19
	v_rsq_f32_e32 v101, v101
	s_nop 0
	v_mul_f32_e32 v50, v50, v101
	v_mul_f32_e32 v51, v51, v101
	v_mul_f32_e32 v52, v52, v101
	v_mul_f32_e32 v53, v53, v101
	v_fma_f32 v50, v50, v6, v10
	v_fma_f32 v51, v51, v7, v11
	v_fma_f32 v52, v52, v8, v12
	v_fma_f32 v53, v53, v9, v13
	v_fma_mix_f32 v50, v58, v54, v50 op_sel_hi:[0,1,0]
	v_fma_mix_f32 v51, v58, v54, v51 op_sel:[0,1,0] op_sel_hi:[0,1,0]
	v_fma_mix_f32 v52, v58, v55, v52 op_sel_hi:[0,1,0]
	v_fma_mix_f32 v53, v58, v55, v53 op_sel:[0,1,0] op_sel_hi:[0,1,0]
	v_fma_mixlo_f16 v102, v50, v56, 0 op_sel_hi:[0,1,0]
	v_fma_mixlo_f16 v104, v51, v56, 0 op_sel:[0,1,0] op_sel_hi:[0,1,0]
	v_fma_mixlo_f16 v103, v52, v57, 0 op_sel_hi:[0,1,0]
	v_fma_mixlo_f16 v105, v53, v57, 0 op_sel:[0,1,0] op_sel_hi:[0,1,0]
	v_and_b32_e32 v102, 0xffff, v102
	v_and_b32_e32 v103, 0xffff, v103
	v_lshl_or_b32 v102, v104, 16, v102
	v_lshl_or_b32 v103, v105, 16, v103
	s_add_i32 s16, s14, 3072
	s_lshl_b32 s19, s16, 11
	s_add_u32 s20, s12, s19
	s_addc_u32 s21, s13, 0
	global_store_dwordx2 v4, v[102:103], s[20:21] sc1
	s_waitcnt vmcnt(16)
	v_add_f32_e32 v100, v60, v61
	v_add_f32_e32 v101, v62, v63
	v_add_f32_e32 v100, v100, v101
	s_nop 1
	v_add_f32_dpp v100, v100, v100 quad_perm:[1,0,3,2] row_mask:0xf bank_mask:0xf bound_ctrl:1
	s_nop 1
	v_add_f32_dpp v100, v100, v100 quad_perm:[2,3,0,1] row_mask:0xf bank_mask:0xf bound_ctrl:1
	s_nop 1
	v_add_f32_dpp v100, v100, v100 row_half_mirror row_mask:0xf bank_mask:0xf bound_ctrl:1
	s_nop 1
	v_add_f32_dpp v100, v100, v100 row_mirror row_mask:0xf bank_mask:0xf bound_ctrl:1
	v_fmac_f32_e32 v60, v100, v14
	v_fmac_f32_e32 v61, v100, v14
	v_fmac_f32_e32 v62, v100, v14
	v_fmac_f32_e32 v63, v100, v14
	v_mul_f32_e32 v101, v60, v60
	v_mul_f32_e32 v102, v62, v62
	v_fmac_f32_e32 v101, v61, v61
	v_fmac_f32_e32 v102, v63, v63
	v_add_f32_e32 v101, v101, v102
	s_nop 1
	v_add_f32_dpp v101, v101, v101 quad_perm:[1,0,3,2] row_mask:0xf bank_mask:0xf bound_ctrl:1
	s_nop 1
	v_add_f32_dpp v101, v101, v101 quad_perm:[2,3,0,1] row_mask:0xf bank_mask:0xf bound_ctrl:1
	s_nop 1
	v_add_f32_dpp v101, v101, v101 row_half_mirror row_mask:0xf bank_mask:0xf bound_ctrl:1
	s_nop 1
	v_add_f32_dpp v101, v101, v101 row_mirror row_mask:0xf bank_mask:0xf bound_ctrl:1
	v_fma_f32 v101, v101, v15, v19
	v_rsq_f32_e32 v101, v101
	s_nop 0
	v_mul_f32_e32 v60, v60, v101
	v_mul_f32_e32 v61, v61, v101
	v_mul_f32_e32 v62, v62, v101
	v_mul_f32_e32 v63, v63, v101
	v_fma_f32 v60, v60, v6, v10
	v_fma_f32 v61, v61, v7, v11
	v_fma_f32 v62, v62, v8, v12
	v_fma_f32 v63, v63, v9, v13
	v_fma_mix_f32 v60, v68, v64, v60 op_sel_hi:[0,1,0]
	v_fma_mix_f32 v61, v68, v64, v61 op_sel:[0,1,0] op_sel_hi:[0,1,0]
	v_fma_mix_f32 v62, v68, v65, v62 op_sel_hi:[0,1,0]
	v_fma_mix_f32 v63, v68, v65, v63 op_sel:[0,1,0] op_sel_hi:[0,1,0]
	v_fma_mixlo_f16 v102, v60, v66, 0 op_sel_hi:[0,1,0]
	v_fma_mixlo_f16 v104, v61, v66, 0 op_sel:[0,1,0] op_sel_hi:[0,1,0]
	v_fma_mixlo_f16 v103, v62, v67, 0 op_sel_hi:[0,1,0]
	v_fma_mixlo_f16 v105, v63, v67, 0 op_sel:[0,1,0] op_sel_hi:[0,1,0]
	v_and_b32_e32 v102, 0xffff, v102
	v_and_b32_e32 v103, 0xffff, v103
	v_lshl_or_b32 v102, v104, 16, v102
	v_lshl_or_b32 v103, v105, 16, v103
	s_add_i32 s16, s14, 4096
	s_lshl_b32 s19, s16, 11
	s_add_u32 s20, s12, s19
	s_addc_u32 s21, s13, 0
	global_store_dwordx2 v4, v[102:103], s[20:21] sc1
	s_waitcnt vmcnt(13)
	v_add_f32_e32 v100, v70, v71
	v_add_f32_e32 v101, v72, v73
	v_add_f32_e32 v100, v100, v101
	s_nop 1
	v_add_f32_dpp v100, v100, v100 quad_perm:[1,0,3,2] row_mask:0xf bank_mask:0xf bound_ctrl:1
	s_nop 1
	v_add_f32_dpp v100, v100, v100 quad_perm:[2,3,0,1] row_mask:0xf bank_mask:0xf bound_ctrl:1
	s_nop 1
	v_add_f32_dpp v100, v100, v100 row_half_mirror row_mask:0xf bank_mask:0xf bound_ctrl:1
	s_nop 1
	v_add_f32_dpp v100, v100, v100 row_mirror row_mask:0xf bank_mask:0xf bound_ctrl:1
	v_fmac_f32_e32 v70, v100, v14
	v_fmac_f32_e32 v71, v100, v14
	v_fmac_f32_e32 v72, v100, v14
	v_fmac_f32_e32 v73, v100, v14
	v_mul_f32_e32 v101, v70, v70
	v_mul_f32_e32 v102, v72, v72
	v_fmac_f32_e32 v101, v71, v71
	v_fmac_f32_e32 v102, v73, v73
	v_add_f32_e32 v101, v101, v102
	s_nop 1
	v_add_f32_dpp v101, v101, v101 quad_perm:[1,0,3,2] row_mask:0xf bank_mask:0xf bound_ctrl:1
	s_nop 1
	v_add_f32_dpp v101, v101, v101 quad_perm:[2,3,0,1] row_mask:0xf bank_mask:0xf bound_ctrl:1
	s_nop 1
	v_add_f32_dpp v101, v101, v101 row_half_mirror row_mask:0xf bank_mask:0xf bound_ctrl:1
	s_nop 1
	v_add_f32_dpp v101, v101, v101 row_mirror row_mask:0xf bank_mask:0xf bound_ctrl:1
	v_fma_f32 v101, v101, v15, v19
	v_rsq_f32_e32 v101, v101
	s_nop 0
	v_mul_f32_e32 v70, v70, v101
	v_mul_f32_e32 v71, v71, v101
	v_mul_f32_e32 v72, v72, v101
	v_mul_f32_e32 v73, v73, v101
	v_fma_f32 v70, v70, v6, v10
	v_fma_f32 v71, v71, v7, v11
	v_fma_f32 v72, v72, v8, v12
	v_fma_f32 v73, v73, v9, v13
	v_fma_mix_f32 v70, v78, v74, v70 op_sel_hi:[0,1,0]
	v_fma_mix_f32 v71, v78, v74, v71 op_sel:[0,1,0] op_sel_hi:[0,1,0]
	v_fma_mix_f32 v72, v78, v75, v72 op_sel_hi:[0,1,0]
	v_fma_mix_f32 v73, v78, v75, v73 op_sel:[0,1,0] op_sel_hi:[0,1,0]
	v_fma_mixlo_f16 v102, v70, v76, 0 op_sel_hi:[0,1,0]
	v_fma_mixlo_f16 v104, v71, v76, 0 op_sel:[0,1,0] op_sel_hi:[0,1,0]
	v_fma_mixlo_f16 v103, v72, v77, 0 op_sel_hi:[0,1,0]
	v_fma_mixlo_f16 v105, v73, v77, 0 op_sel:[0,1,0] op_sel_hi:[0,1,0]
	v_and_b32_e32 v102, 0xffff, v102
	v_and_b32_e32 v103, 0xffff, v103
	v_lshl_or_b32 v102, v104, 16, v102
	v_lshl_or_b32 v103, v105, 16, v103
	s_add_i32 s16, s14, 5120
	s_lshl_b32 s19, s16, 11
	s_add_u32 s20, s12, s19
	s_addc_u32 s21, s13, 0
	global_store_dwordx2 v4, v[102:103], s[20:21] sc1
	s_waitcnt vmcnt(10)
; __device__ __forceinline__ bf16 f2bf(float f) { return (bf16)(pk2(f, 0.f) & 0xffffu); }
; __device__ __forceinline__ float bf2f(bf16 b) { return (float)__builtin_bit_cast(_Float16, b); }
; __device__ __forceinline__ void post_phase(const Ctx& F, const float* gn_g, const float* gn_b) {
;     ...
;     for (int it0 = F.gw * 4; it0 < M * NH; it0 += F.NGW * 4) {
;         float y[4], bsv[4], vv[4], gg[4]; int cc[4]; size_t oo[4];
; #pragma unroll
;         for (int u = 0; u < 4; ++u) { const int it = it0 + u; const int tok = it >> 3, head = it & 7; const int bh = (tok / SEQ) * NH + head, pos = tok & (SEQ - 1);
;             const size_t idx = ((size_t)bh * SEQ + pos) * 64 + lane; cc[u] = head * 64 + lane; oo[u] = (size_t)tok * 1024 + 512 + cc[u];
;             y[u] = Y[idx]; bsv[u] = SCAL[((size_t)bh * SEQ + pos) * 2 + 1]; vv[u] = bf2f(SV[idx]); gg[u] = bf2f(GG[(size_t)tok * 512 + cc[u]]); }
;     ...
;             const float mean = wave_sum_d(y[u]) * (1.f / 64.f); const float d = y[u] - mean; const float var = wave_sum_d(d * d) * (1.f / 64.f);
;             const float yn = d * rsqrtf(var + GN_EPS) * gn_g[cc[u]] + gn_b[cc[u]];
;             CAT[oo[u]] = f2bf((yn + bsv[u] * vv[u]) * gg[u]); }
	v_add_f32_e32 v100, v80, v81
	v_add_f32_e32 v101, v82, v83
	v_add_f32_e32 v100, v100, v101
	s_nop 1
	v_add_f32_dpp v100, v100, v100 quad_perm:[1,0,3,2] row_mask:0xf bank_mask:0xf bound_ctrl:1
	s_nop 1
	v_add_f32_dpp v100, v100, v100 quad_perm:[2,3,0,1] row_mask:0xf bank_mask:0xf bound_ctrl:1
	s_nop 1
	v_add_f32_dpp v100, v100, v100 row_half_mirror row_mask:0xf bank_mask:0xf bound_ctrl:1
	s_nop 1
	v_add_f32_dpp v100, v100, v100 row_mirror row_mask:0xf bank_mask:0xf bound_ctrl:1
	v_fmac_f32_e32 v80, v100, v14
	v_fmac_f32_e32 v81, v100, v14
	v_fmac_f32_e32 v82, v100, v14
	v_fmac_f32_e32 v83, v100, v14
	v_mul_f32_e32 v101, v80, v80
	v_mul_f32_e32 v102, v82, v82
	v_fmac_f32_e32 v101, v81, v81
	v_fmac_f32_e32 v102, v83, v83
	v_add_f32_e32 v101, v101, v102
	s_nop 1
	v_add_f32_dpp v101, v101, v101 quad_perm:[1,0,3,2] row_mask:0xf bank_mask:0xf bound_ctrl:1
	s_nop 1
	v_add_f32_dpp v101, v101, v101 quad_perm:[2,3,0,1] row_mask:0xf bank_mask:0xf bound_ctrl:1
	s_nop 1
	v_add_f32_dpp v101, v101, v101 row_half_mirror row_mask:0xf bank_mask:0xf bound_ctrl:1
	s_nop 1
	v_add_f32_dpp v101, v101, v101 row_mirror row_mask:0xf bank_mask:0xf bound_ctrl:1
	v_fma_f32 v101, v101, v15, v19
	v_rsq_f32_e32 v101, v101
	s_nop 0
	v_mul_f32_e32 v80, v80, v101
	v_mul_f32_e32 v81, v81, v101
	v_mul_f32_e32 v82, v82, v101
	v_mul_f32_e32 v83, v83, v101
	v_fma_f32 v80, v80, v6, v10
	v_fma_f32 v81, v81, v7, v11
	v_fma_f32 v82, v82, v8, v12
	v_fma_f32 v83, v83, v9, v13
	v_fma_mix_f32 v80, v88, v84, v80 op_sel_hi:[0,1,0]
	v_fma_mix_f32 v81, v88, v84, v81 op_sel:[0,1,0] op_sel_hi:[0,1,0]
	v_fma_mix_f32 v82, v88, v85, v82 op_sel_hi:[0,1,0]
	v_fma_mix_f32 v83, v88, v85, v83 op_sel:[0,1,0] op_sel_hi:[0,1,0]
	v_fma_mixlo_f16 v102, v80, v86, 0 op_sel_hi:[0,1,0]
	v_fma_mixlo_f16 v104, v81, v86, 0 op_sel:[0,1,0] op_sel_hi:[0,1,0]
	v_fma_mixlo_f16 v103, v82, v87, 0 op_sel_hi:[0,1,0]
	v_fma_mixlo_f16 v105, v83, v87, 0 op_sel:[0,1,0] op_sel_hi:[0,1,0]
	v_and_b32_e32 v102, 0xffff, v102
	v_and_b32_e32 v103, 0xffff, v103
	v_lshl_or_b32 v102, v104, 16, v102
	v_lshl_or_b32 v103, v105, 16, v103
	s_add_i32 s16, s14, 6144
	s_lshl_b32 s19, s16, 11
	s_add_u32 s20, s12, s19
	s_addc_u32 s21, s13, 0
	global_store_dwordx2 v4, v[102:103], s[20:21] sc1
	s_waitcnt vmcnt(7)
	v_add_f32_e32 v100, v90, v91
	v_add_f32_e32 v101, v92, v93
	v_add_f32_e32 v100, v100, v101
	s_nop 1
	v_add_f32_dpp v100, v100, v100 quad_perm:[1,0,3,2] row_mask:0xf bank_mask:0xf bound_ctrl:1
	s_nop 1
	v_add_f32_dpp v100, v100, v100 quad_perm:[2,3,0,1] row_mask:0xf bank_mask:0xf bound_ctrl:1
	s_nop 1
	v_add_f32_dpp v100, v100, v100 row_half_mirror row_mask:0xf bank_mask:0xf bound_ctrl:1
	s_nop 1
	v_add_f32_dpp v100, v100, v100 row_mirror row_mask:0xf bank_mask:0xf bound_ctrl:1
	v_fmac_f32_e32 v90, v100, v14
	v_fmac_f32_e32 v91, v100, v14
	v_fmac_f32_e32 v92, v100, v14
	v_fmac_f32_e32 v93, v100, v14
	v_mul_f32_e32 v101, v90, v90
	v_mul_f32_e32 v102, v92, v92
	v_fmac_f32_e32 v101, v91, v91
	v_fmac_f32_e32 v102, v93, v93
	v_add_f32_e32 v101, v101, v102
	s_nop 1
	v_add_f32_dpp v101, v101, v101 quad_perm:[1,0,3,2] row_mask:0xf bank_mask:0xf bound_ctrl:1
	s_nop 1
	v_add_f32_dpp v101, v101, v101 quad_perm:[2,3,0,1] row_mask:0xf bank_mask:0xf bound_ctrl:1
	s_nop 1
	v_add_f32_dpp v101, v101, v101 row_half_mirror row_mask:0xf bank_mask:0xf bound_ctrl:1
	s_nop 1
	v_add_f32_dpp v101, v101, v101 row_mirror row_mask:0xf bank_mask:0xf bound_ctrl:1
	v_fma_f32 v101, v101, v15, v19
	v_rsq_f32_e32 v101, v101
	s_nop 0
	v_mul_f32_e32 v90, v90, v101
	v_mul_f32_e32 v91, v91, v101
	v_mul_f32_e32 v92, v92, v101
	v_mul_f32_e32 v93, v93, v101
	v_fma_f32 v90, v90, v6, v10
	v_fma_f32 v91, v91, v7, v11
	v_fma_f32 v92, v92, v8, v12
	v_fma_f32 v93, v93, v9, v13
	v_fma_mix_f32 v90, v98, v94, v90 op_sel_hi:[0,1,0]
	v_fma_mix_f32 v91, v98, v94, v91 op_sel:[0,1,0] op_sel_hi:[0,1,0]
	v_fma_mix_f32 v92, v98, v95, v92 op_sel_hi:[0,1,0]
	v_fma_mix_f32 v93, v98, v95, v93 op_sel:[0,1,0] op_sel_hi:[0,1,0]
	v_fma_mixlo_f16 v102, v90, v96, 0 op_sel_hi:[0,1,0]
	v_fma_mixlo_f16 v104, v91, v96, 0 op_sel:[0,1,0] op_sel_hi:[0,1,0]
	v_fma_mixlo_f16 v103, v92, v97, 0 op_sel_hi:[0,1,0]
	v_fma_mixlo_f16 v105, v93, v97, 0 op_sel:[0,1,0] op_sel_hi:[0,1,0]
	v_and_b32_e32 v102, 0xffff, v102
	v_and_b32_e32 v103, 0xffff, v103
	v_lshl_or_b32 v102, v104, 16, v102
	v_lshl_or_b32 v103, v105, 16, v103
	s_add_i32 s16, s14, 7168
	s_lshl_b32 s19, s16, 11
	s_add_u32 s20, s12, s19
	s_addc_u32 s21, s13, 0
	global_store_dwordx2 v4, v[102:103], s[20:21] sc1
	s_addk_i32 s14, 0x2000
	s_add_i32 s15, s15, 1
	s_cmp_lt_u32 s15, 4
	s_cbranch_scc1 .Lpost_iter
	s_branch .LBB0_773
.Lpost_orig:
	s_add_u32 s0, s72, 0x1ac00000
	s_addc_u32 s1, s73, 0
	s_add_u32 s4, s72, 0x8c00000
	s_addc_u32 s5, s73, 0
	s_add_u32 s8, s72, 0x14c00000
	s_addc_u32 s9, s73, 0
	s_lshl_b32 s10, s87, 2
	s_add_u32 s11, s72, 0x1ec00004
	v_readlane_b32 s6, v253, 1
	s_addc_u32 s12, s73, 0
	s_lshl_b32 s13, s6, 5
	s_add_u32 s14, s72, 0x16c00400
	v_mov_b32_e32 v1, 0
	s_addc_u32 s15, s73, 0
	v_mov_b32_e32 v2, 0xbc800000
	v_mov_b32_e32 v3, 0x3a27c5ac
	v_mov_b32_e32 v4, 0x3c800000
	s_mov_b32 s16, 0x800000
	v_readlane_b32 s7, v253, 2
